# WY producer step 2 (waves 0-3): decay/mask loop rewritten by hand without the per-element 32-register accumulator copies
# speedup vs baseline: 1.0294x; 1.0033x over previous
; #define LAS __attribute__((address_space(3)))
; __device__ __forceinline__ int crow(int r, int hi) { return (r & 3) + 8 * (r >> 2) + 4 * hi; }
; __device__ __forceinline__ int wy_producer_task(const Ctx& c, int l, int tk, WyPre& P, unsigned* head) {
;     ...
;         f32x16 p0, p1; nsa_qk(p0, p1, KIMG, qr, r32, hi);
;         const float gci = GC[i], bei = BE[i];
; #pragma unroll
;         for (int r = 0; r < 16; ++r) { const int j0 = crow(r, hi), j1 = j0 + 32; const float e0 = __expf(fminf(gci - GC[j0], 0.f)), e1 = __expf(fminf(gci - GC[j1], 0.f));
;             if (!isq) { LAS float* lp = LM + (i >> 2) * WY_BS + (r & 3) * WY_QS + (2 * (r >> 2) + hi) * 4 + (i & 3);
;                 lp[0] = (j0 < i) ? bei * p0[r] * e0 : 0.f; lp[32] = (j1 < i) ? bei * p1[r] * e1 : 0.f; }
;             else { p0[r] = (j0 <= i) ? p0[r] * e0 : 0.f; p1[r] = (j1 <= i) ? p1[r] * e1 : 0.f; } }
.LBB0_975:
	s_andn2_b64 vcc, exec, s[2:3]
	v_and_b32_e32 v0, 3, v88
	s_cbranch_vccnz .LBB0_1040
	v_or_b32_e32 v125, s58, v123
	v_mul_u32_u24_e32 v2, 0x104, v125
	v_and_b32_e32 v3, 0xffffffe0, v88
	v_add3_u32 v46, s59, v2, v3
	v_lshlrev_b32_e32 v2, 10, v124
	v_lshlrev_b32_e32 v3, 4, v123
	v_readlane_b32 s2, v254, 32
	v_lshlrev_b32_e32 v128, 2, v124
	v_add_u32_e32 v66, 32, v128
	v_add3_u32 v47, s2, v2, v3
	ds_read_b128 v[2:5], v47
	ds_read2_b32 v[6:7], v46 offset1:1
	ds_read2_b32 v[8:9], v46 offset0:2 offset1:3
	ds_read2_b32 v[10:11], v46 offset0:4 offset1:5
	ds_read2_b32 v[12:13], v46 offset0:6 offset1:7
	ds_read_b128 v[22:25], v47 offset:512
	ds_read_b128 v[34:37], v47 offset:2048
	ds_read2_b32 v[38:39], v46 offset0:16 offset1:17
	ds_read2_b32 v[40:41], v46 offset0:18 offset1:19
	ds_read2_b32 v[42:43], v46 offset0:20 offset1:21
	ds_read2_b32 v[44:45], v46 offset0:22 offset1:23
	s_waitcnt lgkmcnt(9)
	v_cvt_pk_bf16_f32 v18, v6, v7
	s_waitcnt lgkmcnt(8)
	v_cvt_pk_bf16_f32 v19, v8, v9
	s_waitcnt lgkmcnt(7)
	v_cvt_pk_bf16_f32 v20, v10, v11
	s_waitcnt lgkmcnt(6)
	v_cvt_pk_bf16_f32 v21, v12, v13
	s_waitcnt lgkmcnt(3)
	v_cvt_pk_bf16_f32 v38, v38, v39
	s_waitcnt lgkmcnt(2)
	v_cvt_pk_bf16_f32 v39, v40, v41
	s_waitcnt lgkmcnt(1)
	v_cvt_pk_bf16_f32 v40, v42, v43
	s_waitcnt lgkmcnt(0)
	v_cvt_pk_bf16_f32 v41, v44, v45
	ds_read_b128 v[42:45], v47 offset:2560
	v_mfma_f32_32x32x16_bf16 v[2:17], v[2:5], v[18:21], 0
	s_add_i32 s2, 0, 0x11b00
	v_lshl_add_u32 v130, v124, 4, s2
	s_and_b64 vcc, exec, s[80:81]
	v_mfma_f32_32x32x16_bf16 v[18:33], v[22:25], v[18:21], 0
	v_mfma_f32_32x32x16_bf16 v[2:17], v[34:37], v[38:41], v[2:17]
	s_waitcnt lgkmcnt(0)
	v_mfma_f32_32x32x16_bf16 v[18:33], v[42:45], v[38:41], v[18:33]
	ds_read_b128 v[34:37], v47 offset:4096
	ds_read2_b32 v[38:39], v46 offset0:32 offset1:33
	ds_read2_b32 v[40:41], v46 offset0:34 offset1:35
	ds_read2_b32 v[42:43], v46 offset0:36 offset1:37
	ds_read2_b32 v[44:45], v46 offset0:38 offset1:39
	s_waitcnt lgkmcnt(3)
	v_cvt_pk_bf16_f32 v38, v38, v39
	s_waitcnt lgkmcnt(2)
	v_cvt_pk_bf16_f32 v39, v40, v41
	s_waitcnt lgkmcnt(1)
	v_cvt_pk_bf16_f32 v40, v42, v43
	s_waitcnt lgkmcnt(0)
	v_cvt_pk_bf16_f32 v41, v44, v45
	ds_read_b128 v[42:45], v47 offset:4608
	s_nop 0
	v_mfma_f32_32x32x16_bf16 v[2:17], v[34:37], v[38:41], v[2:17]
	ds_read_b128 v[34:37], v47 offset:6144
	s_waitcnt lgkmcnt(1)
	v_mfma_f32_32x32x16_bf16 v[18:33], v[42:45], v[38:41], v[18:33]
	ds_read2_b32 v[38:39], v46 offset0:48 offset1:49
	ds_read2_b32 v[40:41], v46 offset0:50 offset1:51
	ds_read2_b32 v[42:43], v46 offset0:52 offset1:53
	ds_read2_b32 v[44:45], v46 offset0:54 offset1:55
	s_waitcnt lgkmcnt(3)
	v_cvt_pk_bf16_f32 v38, v38, v39
	s_waitcnt lgkmcnt(2)
	v_cvt_pk_bf16_f32 v39, v40, v41
	s_waitcnt lgkmcnt(1)
	v_cvt_pk_bf16_f32 v40, v42, v43
	s_waitcnt lgkmcnt(0)
	v_cvt_pk_bf16_f32 v41, v44, v45
	ds_read_b128 v[42:45], v47 offset:6656
	s_nop 0
	v_mfma_f32_32x32x16_bf16 v[2:17], v[34:37], v[38:41], v[2:17]
	v_lshlrev_b32_e32 v34, 2, v125
	v_add_u32_e32 v35, s2, v34
	v_add_u32_e32 v34, 0, v34
	v_add_u32_e32 v36, 0x11c00, v34
	ds_read_b32 v127, v35
	ds_read_b32 v126, v36
	ds_read2_b32 v[34:35], v130 offset1:32
	s_waitcnt lgkmcnt(3)
	v_mfma_f32_32x32x16_bf16 v[18:33], v[42:45], v[38:41], v[18:33]
	s_waitcnt lgkmcnt(0)
	v_lshrrev_b32_e32 v69, 2, v125
	s_movk_i32 s4, 0x440
	v_mad_u32_u24 v129, v69, s4, 0
	v_sub_u32_e32 v70, v125, v128
	ds_read2_b32 v[46:47], v130 offset0:8 offset1:40
	ds_read2_b32 v[48:49], v130 offset0:9 offset1:41
	ds_read2_b32 v[50:51], v130 offset0:10 offset1:42
	ds_read2_b32 v[52:53], v130 offset0:11 offset1:43
	ds_read2_b32 v[38:39], v130 offset0:0 offset1:32
	ds_read2_b32 v[40:41], v130 offset0:1 offset1:33
	ds_read2_b32 v[42:43], v130 offset0:2 offset1:34
	ds_read2_b32 v[44:45], v130 offset0:3 offset1:35
	s_and_b64 vcc, exec, s[80:81]
	s_cbranch_vccnz .Lwy2_isq
	v_lshlrev_b32_e32 v34, 4, v124
	v_lshlrev_b32_e32 v35, 2, v0
	v_add3_u32 v34, v129, v34, v35
	v_add_u32_e32 v36, 0x8600, v34
	v_add_u32_e32 v37, 0x8820, v34
	s_waitcnt lgkmcnt(0)
	ds_read2_b32 v[54:55], v130 offset0:16 offset1:48
	ds_read2_b32 v[56:57], v130 offset0:17 offset1:49
	ds_read2_b32 v[58:59], v130 offset0:18 offset1:50
	ds_read2_b32 v[60:61], v130 offset0:19 offset1:51
	v_sub_f32_e32 v38, v127, v38
	v_sub_f32_e32 v39, v127, v39
	v_sub_f32_e32 v40, v127, v40
	v_sub_f32_e32 v41, v127, v41
	v_sub_f32_e32 v42, v127, v42
	v_sub_f32_e32 v43, v127, v43
	v_sub_f32_e32 v44, v127, v44
	v_sub_f32_e32 v45, v127, v45
	v_min_f32_e32 v38, 0, v38
	v_min_f32_e32 v39, 0, v39
	v_min_f32_e32 v40, 0, v40
	v_min_f32_e32 v41, 0, v41
	v_min_f32_e32 v42, 0, v42
	v_min_f32_e32 v43, 0, v43
	v_min_f32_e32 v44, 0, v44
	v_min_f32_e32 v45, 0, v45
	v_mul_f32_e32 v38, 0x3fb8aa3b, v38
	v_mul_f32_e32 v39, 0x3fb8aa3b, v39
	v_mul_f32_e32 v40, 0x3fb8aa3b, v40
	v_mul_f32_e32 v41, 0x3fb8aa3b, v41
	v_mul_f32_e32 v42, 0x3fb8aa3b, v42
	v_mul_f32_e32 v43, 0x3fb8aa3b, v43
	v_mul_f32_e32 v44, 0x3fb8aa3b, v44
	v_mul_f32_e32 v45, 0x3fb8aa3b, v45
	v_exp_f32_e32 v38, v38
	v_exp_f32_e32 v39, v39
	v_exp_f32_e32 v40, v40
	v_exp_f32_e32 v41, v41
	v_exp_f32_e32 v42, v42
	v_exp_f32_e32 v43, v43
	v_exp_f32_e32 v44, v44
	v_exp_f32_e32 v45, v45
	v_mul_f32_e32 v72, v2, v126
	v_mul_f32_e32 v73, v18, v126
	v_mul_f32_e32 v74, v3, v126
	v_mul_f32_e32 v75, v19, v126
	v_mul_f32_e32 v76, v4, v126
	v_mul_f32_e32 v77, v20, v126
	v_mul_f32_e32 v78, v5, v126
	v_mul_f32_e32 v79, v21, v126
	v_mul_f32_e32 v72, v72, v38
	v_mul_f32_e32 v73, v73, v39
	v_mul_f32_e32 v74, v74, v40
	v_mul_f32_e32 v75, v75, v41
	v_mul_f32_e32 v76, v76, v42
	v_mul_f32_e32 v77, v77, v43
	v_mul_f32_e32 v78, v78, v44
	v_mul_f32_e32 v79, v79, v45
	v_cmp_lt_i32_e32 vcc, 0, v70
	s_nop 1
	v_cndmask_b32_e32 v72, 0, v72, vcc
	v_cmp_lt_i32_e32 vcc, 32, v70
	s_nop 1
	v_cndmask_b32_e32 v73, 0, v73, vcc
	ds_write2_b32 v36, v72, v73 offset0:0 offset1:32
	v_cmp_lt_i32_e32 vcc, 1, v70
	s_nop 1
	v_cndmask_b32_e32 v74, 0, v74, vcc
	v_cmp_lt_i32_e32 vcc, 33, v70
	s_nop 1
	v_cndmask_b32_e32 v75, 0, v75, vcc
	ds_write2_b32 v36, v74, v75 offset0:68 offset1:100
	v_cmp_lt_i32_e32 vcc, 2, v70
	s_nop 1
	v_cndmask_b32_e32 v76, 0, v76, vcc
	v_cmp_lt_i32_e32 vcc, 34, v70
	s_nop 1
	v_cndmask_b32_e32 v77, 0, v77, vcc
	ds_write2_b32 v37, v76, v77 offset0:0 offset1:32
	v_cmp_lt_i32_e32 vcc, 3, v70
	s_nop 1
	v_cndmask_b32_e32 v78, 0, v78, vcc
	v_cmp_lt_i32_e32 vcc, 35, v70
	s_nop 1
	v_cndmask_b32_e32 v79, 0, v79, vcc
	ds_write2_b32 v37, v78, v79 offset0:68 offset1:100
	ds_read2_b32 v[62:63], v130 offset0:24 offset1:56
	ds_read2_b32 v[64:65], v130 offset0:25 offset1:57
	ds_read2_b32 v[66:67], v130 offset0:26 offset1:58
	ds_read2_b32 v[68:69], v130 offset0:27 offset1:59
	s_waitcnt lgkmcnt(4)
; #define LAS __attribute__((address_space(3)))
; __device__ __forceinline__ int crow(int r, int hi) { return (r & 3) + 8 * (r >> 2) + 4 * hi; }
; __device__ __forceinline__ int wy_producer_task(const Ctx& c, int l, int tk, WyPre& P, unsigned* head) {
;     ...
;         for (int r = 0; r < 16; ++r) { const int j0 = crow(r, hi), j1 = j0 + 32; const float e0 = __expf(fminf(gci - GC[j0], 0.f)), e1 = __expf(fminf(gci - GC[j1], 0.f));
;             if (!isq) { LAS float* lp = LM + (i >> 2) * WY_BS + (r & 3) * WY_QS + (2 * (r >> 2) + hi) * 4 + (i & 3);
;                 lp[0] = (j0 < i) ? bei * p0[r] * e0 : 0.f; lp[32] = (j1 < i) ? bei * p1[r] * e1 : 0.f; }
	v_sub_f32_e32 v46, v127, v46
	v_sub_f32_e32 v47, v127, v47
	v_sub_f32_e32 v48, v127, v48
	v_sub_f32_e32 v49, v127, v49
	v_sub_f32_e32 v50, v127, v50
	v_sub_f32_e32 v51, v127, v51
	v_sub_f32_e32 v52, v127, v52
	v_sub_f32_e32 v53, v127, v53
	v_min_f32_e32 v46, 0, v46
	v_min_f32_e32 v47, 0, v47
	v_min_f32_e32 v48, 0, v48
	v_min_f32_e32 v49, 0, v49
	v_min_f32_e32 v50, 0, v50
	v_min_f32_e32 v51, 0, v51
	v_min_f32_e32 v52, 0, v52
	v_min_f32_e32 v53, 0, v53
	v_mul_f32_e32 v46, 0x3fb8aa3b, v46
	v_mul_f32_e32 v47, 0x3fb8aa3b, v47
	v_mul_f32_e32 v48, 0x3fb8aa3b, v48
	v_mul_f32_e32 v49, 0x3fb8aa3b, v49
	v_mul_f32_e32 v50, 0x3fb8aa3b, v50
	v_mul_f32_e32 v51, 0x3fb8aa3b, v51
	v_mul_f32_e32 v52, 0x3fb8aa3b, v52
	v_mul_f32_e32 v53, 0x3fb8aa3b, v53
	v_exp_f32_e32 v46, v46
	v_exp_f32_e32 v47, v47
	v_exp_f32_e32 v48, v48
	v_exp_f32_e32 v49, v49
	v_exp_f32_e32 v50, v50
	v_exp_f32_e32 v51, v51
	v_exp_f32_e32 v52, v52
	v_exp_f32_e32 v53, v53
	v_mul_f32_e32 v72, v6, v126
	v_mul_f32_e32 v73, v22, v126
	v_mul_f32_e32 v74, v7, v126
	v_mul_f32_e32 v75, v23, v126
	v_mul_f32_e32 v76, v8, v126
	v_mul_f32_e32 v77, v24, v126
	v_mul_f32_e32 v78, v9, v126
	v_mul_f32_e32 v79, v25, v126
	v_mul_f32_e32 v72, v72, v46
	v_mul_f32_e32 v73, v73, v47
	v_mul_f32_e32 v74, v74, v48
	v_mul_f32_e32 v75, v75, v49
	v_mul_f32_e32 v76, v76, v50
	v_mul_f32_e32 v77, v77, v51
	v_mul_f32_e32 v78, v78, v52
	v_mul_f32_e32 v79, v79, v53
	v_cmp_lt_i32_e32 vcc, 8, v70
	s_nop 1
	v_cndmask_b32_e32 v72, 0, v72, vcc
	v_cmp_lt_i32_e32 vcc, 40, v70
	s_nop 1
	v_cndmask_b32_e32 v73, 0, v73, vcc
	ds_write2_b32 v36, v72, v73 offset0:8 offset1:40
	v_cmp_lt_i32_e32 vcc, 9, v70
	s_nop 1
	v_cndmask_b32_e32 v74, 0, v74, vcc
	v_cmp_lt_i32_e32 vcc, 41, v70
	s_nop 1
	v_cndmask_b32_e32 v75, 0, v75, vcc
	ds_write2_b32 v36, v74, v75 offset0:76 offset1:108
	v_cmp_lt_i32_e32 vcc, 10, v70
	s_nop 1
	v_cndmask_b32_e32 v76, 0, v76, vcc
	v_cmp_lt_i32_e32 vcc, 42, v70
	s_nop 1
	v_cndmask_b32_e32 v77, 0, v77, vcc
	ds_write2_b32 v37, v76, v77 offset0:8 offset1:40
	v_cmp_lt_i32_e32 vcc, 11, v70
	s_nop 1
	v_cndmask_b32_e32 v78, 0, v78, vcc
	v_cmp_lt_i32_e32 vcc, 43, v70
	s_nop 1
	v_cndmask_b32_e32 v79, 0, v79, vcc
	ds_write2_b32 v37, v78, v79 offset0:76 offset1:108
	s_waitcnt lgkmcnt(4)
	v_sub_f32_e32 v54, v127, v54
	v_sub_f32_e32 v55, v127, v55
	v_sub_f32_e32 v56, v127, v56
	v_sub_f32_e32 v57, v127, v57
	v_sub_f32_e32 v58, v127, v58
	v_sub_f32_e32 v59, v127, v59
	v_sub_f32_e32 v60, v127, v60
	v_sub_f32_e32 v61, v127, v61
	v_min_f32_e32 v54, 0, v54
	v_min_f32_e32 v55, 0, v55
	v_min_f32_e32 v56, 0, v56
	v_min_f32_e32 v57, 0, v57
	v_min_f32_e32 v58, 0, v58
	v_min_f32_e32 v59, 0, v59
	v_min_f32_e32 v60, 0, v60
	v_min_f32_e32 v61, 0, v61
	v_mul_f32_e32 v54, 0x3fb8aa3b, v54
	v_mul_f32_e32 v55, 0x3fb8aa3b, v55
	v_mul_f32_e32 v56, 0x3fb8aa3b, v56
	v_mul_f32_e32 v57, 0x3fb8aa3b, v57
	v_mul_f32_e32 v58, 0x3fb8aa3b, v58
	v_mul_f32_e32 v59, 0x3fb8aa3b, v59
	v_mul_f32_e32 v60, 0x3fb8aa3b, v60
	v_mul_f32_e32 v61, 0x3fb8aa3b, v61
	v_exp_f32_e32 v54, v54
	v_exp_f32_e32 v55, v55
	v_exp_f32_e32 v56, v56
	v_exp_f32_e32 v57, v57
	v_exp_f32_e32 v58, v58
	v_exp_f32_e32 v59, v59
	v_exp_f32_e32 v60, v60
	v_exp_f32_e32 v61, v61
	v_mul_f32_e32 v72, v10, v126
	v_mul_f32_e32 v73, v26, v126
	v_mul_f32_e32 v74, v11, v126
	v_mul_f32_e32 v75, v27, v126
	v_mul_f32_e32 v76, v12, v126
	v_mul_f32_e32 v77, v28, v126
	v_mul_f32_e32 v78, v13, v126
	v_mul_f32_e32 v79, v29, v126
	v_mul_f32_e32 v72, v72, v54
	v_mul_f32_e32 v73, v73, v55
	v_mul_f32_e32 v74, v74, v56
	v_mul_f32_e32 v75, v75, v57
	v_mul_f32_e32 v76, v76, v58
	v_mul_f32_e32 v77, v77, v59
	v_mul_f32_e32 v78, v78, v60
	v_mul_f32_e32 v79, v79, v61
	v_cmp_lt_i32_e32 vcc, 16, v70
	s_nop 1
	v_cndmask_b32_e32 v72, 0, v72, vcc
	v_cmp_lt_i32_e32 vcc, 48, v70
	s_nop 1
	v_cndmask_b32_e32 v73, 0, v73, vcc
	ds_write2_b32 v36, v72, v73 offset0:16 offset1:48
	v_cmp_lt_i32_e32 vcc, 17, v70
	s_nop 1
	v_cndmask_b32_e32 v74, 0, v74, vcc
	v_cmp_lt_i32_e32 vcc, 49, v70
	s_nop 1
	v_cndmask_b32_e32 v75, 0, v75, vcc
	ds_write2_b32 v36, v74, v75 offset0:84 offset1:116
	v_cmp_lt_i32_e32 vcc, 18, v70
	s_nop 1
	v_cndmask_b32_e32 v76, 0, v76, vcc
	v_cmp_lt_i32_e32 vcc, 50, v70
	s_nop 1
	v_cndmask_b32_e32 v77, 0, v77, vcc
	ds_write2_b32 v37, v76, v77 offset0:16 offset1:48
	v_cmp_lt_i32_e32 vcc, 19, v70
	s_nop 1
	v_cndmask_b32_e32 v78, 0, v78, vcc
	v_cmp_lt_i32_e32 vcc, 51, v70
	s_nop 1
	v_cndmask_b32_e32 v79, 0, v79, vcc
	ds_write2_b32 v37, v78, v79 offset0:84 offset1:116
	s_waitcnt lgkmcnt(0)
	v_sub_f32_e32 v62, v127, v62
	v_sub_f32_e32 v63, v127, v63
	v_sub_f32_e32 v64, v127, v64
	v_sub_f32_e32 v65, v127, v65
	v_sub_f32_e32 v66, v127, v66
	v_sub_f32_e32 v67, v127, v67
	v_sub_f32_e32 v68, v127, v68
	v_sub_f32_e32 v69, v127, v69
	v_min_f32_e32 v62, 0, v62
	v_min_f32_e32 v63, 0, v63
	v_min_f32_e32 v64, 0, v64
	v_min_f32_e32 v65, 0, v65
	v_min_f32_e32 v66, 0, v66
	v_min_f32_e32 v67, 0, v67
	v_min_f32_e32 v68, 0, v68
	v_min_f32_e32 v69, 0, v69
	v_mul_f32_e32 v62, 0x3fb8aa3b, v62
	v_mul_f32_e32 v63, 0x3fb8aa3b, v63
	v_mul_f32_e32 v64, 0x3fb8aa3b, v64
	v_mul_f32_e32 v65, 0x3fb8aa3b, v65
	v_mul_f32_e32 v66, 0x3fb8aa3b, v66
	v_mul_f32_e32 v67, 0x3fb8aa3b, v67
	v_mul_f32_e32 v68, 0x3fb8aa3b, v68
	v_mul_f32_e32 v69, 0x3fb8aa3b, v69
	v_exp_f32_e32 v62, v62
	v_exp_f32_e32 v63, v63
	v_exp_f32_e32 v64, v64
	v_exp_f32_e32 v65, v65
	v_exp_f32_e32 v66, v66
	v_exp_f32_e32 v67, v67
	v_exp_f32_e32 v68, v68
	v_exp_f32_e32 v69, v69
	v_mul_f32_e32 v72, v14, v126
	v_mul_f32_e32 v73, v30, v126
	v_mul_f32_e32 v74, v15, v126
	v_mul_f32_e32 v75, v31, v126
	v_mul_f32_e32 v76, v16, v126
	v_mul_f32_e32 v77, v32, v126
	v_mul_f32_e32 v78, v17, v126
	v_mul_f32_e32 v79, v33, v126
	v_mul_f32_e32 v72, v72, v62
	v_mul_f32_e32 v73, v73, v63
	v_mul_f32_e32 v74, v74, v64
	v_mul_f32_e32 v75, v75, v65
	v_mul_f32_e32 v76, v76, v66
	v_mul_f32_e32 v77, v77, v67
	v_mul_f32_e32 v78, v78, v68
	v_mul_f32_e32 v79, v79, v69
	v_cmp_lt_i32_e32 vcc, 24, v70
	s_nop 1
	v_cndmask_b32_e32 v72, 0, v72, vcc
	v_cmp_lt_i32_e32 vcc, 56, v70
	s_nop 1
	v_cndmask_b32_e32 v73, 0, v73, vcc
	ds_write2_b32 v36, v72, v73 offset0:24 offset1:56
	v_cmp_lt_i32_e32 vcc, 25, v70
	s_nop 1
	v_cndmask_b32_e32 v74, 0, v74, vcc
	v_cmp_lt_i32_e32 vcc, 57, v70
	s_nop 1
	v_cndmask_b32_e32 v75, 0, v75, vcc
	ds_write2_b32 v36, v74, v75 offset0:92 offset1:124
	v_cmp_lt_i32_e32 vcc, 26, v70
	s_nop 1
	v_cndmask_b32_e32 v76, 0, v76, vcc
	v_cmp_lt_i32_e32 vcc, 58, v70
	s_nop 1
	v_cndmask_b32_e32 v77, 0, v77, vcc
	ds_write2_b32 v37, v76, v77 offset0:24 offset1:56
	v_cmp_lt_i32_e32 vcc, 27, v70
	s_nop 1
	v_cndmask_b32_e32 v78, 0, v78, vcc
	v_cmp_lt_i32_e32 vcc, 59, v70
	s_nop 1
	v_cndmask_b32_e32 v79, 0, v79, vcc
	ds_write2_b32 v37, v78, v79 offset0:92 offset1:124
	s_branch .LBB0_1040
; __device__ __forceinline__ int wy_producer_task(const Ctx& c, int l, int tk, WyPre& P, unsigned* head) {
;     ...
;             else { p0[r] = (j0 <= i) ? p0[r] * e0 : 0.f; p1[r] = (j1 <= i) ? p1[r] * e1 : 0.f; } }
.Lwy2_isq:
	s_waitcnt lgkmcnt(0)
	ds_read2_b32 v[54:55], v130 offset0:16 offset1:48
	ds_read2_b32 v[56:57], v130 offset0:17 offset1:49
	ds_read2_b32 v[58:59], v130 offset0:18 offset1:50
	ds_read2_b32 v[60:61], v130 offset0:19 offset1:51
	v_sub_f32_e32 v38, v127, v38
	v_sub_f32_e32 v39, v127, v39
	v_sub_f32_e32 v40, v127, v40
	v_sub_f32_e32 v41, v127, v41
	v_sub_f32_e32 v42, v127, v42
	v_sub_f32_e32 v43, v127, v43
	v_sub_f32_e32 v44, v127, v44
	v_sub_f32_e32 v45, v127, v45
	v_min_f32_e32 v38, 0, v38
	v_min_f32_e32 v39, 0, v39
	v_min_f32_e32 v40, 0, v40
	v_min_f32_e32 v41, 0, v41
	v_min_f32_e32 v42, 0, v42
	v_min_f32_e32 v43, 0, v43
	v_min_f32_e32 v44, 0, v44
	v_min_f32_e32 v45, 0, v45
	v_mul_f32_e32 v38, 0x3fb8aa3b, v38
	v_mul_f32_e32 v39, 0x3fb8aa3b, v39
	v_mul_f32_e32 v40, 0x3fb8aa3b, v40
	v_mul_f32_e32 v41, 0x3fb8aa3b, v41
	v_mul_f32_e32 v42, 0x3fb8aa3b, v42
	v_mul_f32_e32 v43, 0x3fb8aa3b, v43
	v_mul_f32_e32 v44, 0x3fb8aa3b, v44
	v_mul_f32_e32 v45, 0x3fb8aa3b, v45
	v_exp_f32_e32 v38, v38
	v_exp_f32_e32 v39, v39
	v_exp_f32_e32 v40, v40
	v_exp_f32_e32 v41, v41
	v_exp_f32_e32 v42, v42
	v_exp_f32_e32 v43, v43
	v_exp_f32_e32 v44, v44
	v_exp_f32_e32 v45, v45
	v_mul_f32_e32 v2, v2, v38
	v_mul_f32_e32 v18, v18, v39
	v_mul_f32_e32 v3, v3, v40
	v_mul_f32_e32 v19, v19, v41
	v_mul_f32_e32 v4, v4, v42
	v_mul_f32_e32 v20, v20, v43
	v_mul_f32_e32 v5, v5, v44
	v_mul_f32_e32 v21, v21, v45
	v_cmp_le_i32_e32 vcc, 0, v70
	s_nop 1
	v_cndmask_b32_e32 v2, 0, v2, vcc
	v_cmp_le_i32_e32 vcc, 32, v70
	s_nop 1
	v_cndmask_b32_e32 v18, 0, v18, vcc
	v_cmp_le_i32_e32 vcc, 1, v70
	s_nop 1
	v_cndmask_b32_e32 v3, 0, v3, vcc
	v_cmp_le_i32_e32 vcc, 33, v70
	s_nop 1
	v_cndmask_b32_e32 v19, 0, v19, vcc
	v_cmp_le_i32_e32 vcc, 2, v70
	s_nop 1
	v_cndmask_b32_e32 v4, 0, v4, vcc
	v_cmp_le_i32_e32 vcc, 34, v70
	s_nop 1
	v_cndmask_b32_e32 v20, 0, v20, vcc
	v_cmp_le_i32_e32 vcc, 3, v70
	s_nop 1
	v_cndmask_b32_e32 v5, 0, v5, vcc
	v_cmp_le_i32_e32 vcc, 35, v70
	s_nop 1
	v_cndmask_b32_e32 v21, 0, v21, vcc
	ds_read2_b32 v[62:63], v130 offset0:24 offset1:56
	ds_read2_b32 v[64:65], v130 offset0:25 offset1:57
	ds_read2_b32 v[66:67], v130 offset0:26 offset1:58
	ds_read2_b32 v[68:69], v130 offset0:27 offset1:59
	s_waitcnt lgkmcnt(4)
	v_sub_f32_e32 v46, v127, v46
	v_sub_f32_e32 v47, v127, v47
	v_sub_f32_e32 v48, v127, v48
	v_sub_f32_e32 v49, v127, v49
	v_sub_f32_e32 v50, v127, v50
	v_sub_f32_e32 v51, v127, v51
	v_sub_f32_e32 v52, v127, v52
	v_sub_f32_e32 v53, v127, v53
	v_min_f32_e32 v46, 0, v46
	v_min_f32_e32 v47, 0, v47
	v_min_f32_e32 v48, 0, v48
	v_min_f32_e32 v49, 0, v49
	v_min_f32_e32 v50, 0, v50
	v_min_f32_e32 v51, 0, v51
	v_min_f32_e32 v52, 0, v52
	v_min_f32_e32 v53, 0, v53
	v_mul_f32_e32 v46, 0x3fb8aa3b, v46
	v_mul_f32_e32 v47, 0x3fb8aa3b, v47
	v_mul_f32_e32 v48, 0x3fb8aa3b, v48
	v_mul_f32_e32 v49, 0x3fb8aa3b, v49
	v_mul_f32_e32 v50, 0x3fb8aa3b, v50
	v_mul_f32_e32 v51, 0x3fb8aa3b, v51
	v_mul_f32_e32 v52, 0x3fb8aa3b, v52
	v_mul_f32_e32 v53, 0x3fb8aa3b, v53
	v_exp_f32_e32 v46, v46
	v_exp_f32_e32 v47, v47
	v_exp_f32_e32 v48, v48
	v_exp_f32_e32 v49, v49
	v_exp_f32_e32 v50, v50
	v_exp_f32_e32 v51, v51
	v_exp_f32_e32 v52, v52
	v_exp_f32_e32 v53, v53
	v_mul_f32_e32 v6, v6, v46
	v_mul_f32_e32 v22, v22, v47
	v_mul_f32_e32 v7, v7, v48
	v_mul_f32_e32 v23, v23, v49
	v_mul_f32_e32 v8, v8, v50
	v_mul_f32_e32 v24, v24, v51
	v_mul_f32_e32 v9, v9, v52
	v_mul_f32_e32 v25, v25, v53
	v_cmp_le_i32_e32 vcc, 8, v70
	s_nop 1
	v_cndmask_b32_e32 v6, 0, v6, vcc
	v_cmp_le_i32_e32 vcc, 40, v70
	s_nop 1
	v_cndmask_b32_e32 v22, 0, v22, vcc
	v_cmp_le_i32_e32 vcc, 9, v70
	s_nop 1
	v_cndmask_b32_e32 v7, 0, v7, vcc
	v_cmp_le_i32_e32 vcc, 41, v70
	s_nop 1
	v_cndmask_b32_e32 v23, 0, v23, vcc
	v_cmp_le_i32_e32 vcc, 10, v70
	s_nop 1
	v_cndmask_b32_e32 v8, 0, v8, vcc
	v_cmp_le_i32_e32 vcc, 42, v70
	s_nop 1
	v_cndmask_b32_e32 v24, 0, v24, vcc
	v_cmp_le_i32_e32 vcc, 11, v70
	s_nop 1
	v_cndmask_b32_e32 v9, 0, v9, vcc
	v_cmp_le_i32_e32 vcc, 43, v70
	s_nop 1
	v_cndmask_b32_e32 v25, 0, v25, vcc
	s_waitcnt lgkmcnt(4)
; __device__ __forceinline__ int wy_producer_task(const Ctx& c, int l, int tk, WyPre& P, unsigned* head) {
;     ...
;             else { p0[r] = (j0 <= i) ? p0[r] * e0 : 0.f; p1[r] = (j1 <= i) ? p1[r] * e1 : 0.f; } }
;         if (isq) { u32x4 pw[4]; pack_p(p0, p1, pw); store_p(PKm + ((size_t)2 * 2048 + tk) * 512, rt, lane, pw); }
	v_sub_f32_e32 v54, v127, v54
	v_sub_f32_e32 v55, v127, v55
	v_sub_f32_e32 v56, v127, v56
	v_sub_f32_e32 v57, v127, v57
	v_sub_f32_e32 v58, v127, v58
	v_sub_f32_e32 v59, v127, v59
	v_sub_f32_e32 v60, v127, v60
	v_sub_f32_e32 v61, v127, v61
	v_min_f32_e32 v54, 0, v54
	v_min_f32_e32 v55, 0, v55
	v_min_f32_e32 v56, 0, v56
	v_min_f32_e32 v57, 0, v57
	v_min_f32_e32 v58, 0, v58
	v_min_f32_e32 v59, 0, v59
	v_min_f32_e32 v60, 0, v60
	v_min_f32_e32 v61, 0, v61
	v_mul_f32_e32 v54, 0x3fb8aa3b, v54
	v_mul_f32_e32 v55, 0x3fb8aa3b, v55
	v_mul_f32_e32 v56, 0x3fb8aa3b, v56
	v_mul_f32_e32 v57, 0x3fb8aa3b, v57
	v_mul_f32_e32 v58, 0x3fb8aa3b, v58
	v_mul_f32_e32 v59, 0x3fb8aa3b, v59
	v_mul_f32_e32 v60, 0x3fb8aa3b, v60
	v_mul_f32_e32 v61, 0x3fb8aa3b, v61
	v_exp_f32_e32 v54, v54
	v_exp_f32_e32 v55, v55
	v_exp_f32_e32 v56, v56
	v_exp_f32_e32 v57, v57
	v_exp_f32_e32 v58, v58
	v_exp_f32_e32 v59, v59
	v_exp_f32_e32 v60, v60
	v_exp_f32_e32 v61, v61
	v_mul_f32_e32 v10, v10, v54
	v_mul_f32_e32 v26, v26, v55
	v_mul_f32_e32 v11, v11, v56
	v_mul_f32_e32 v27, v27, v57
	v_mul_f32_e32 v12, v12, v58
	v_mul_f32_e32 v28, v28, v59
	v_mul_f32_e32 v13, v13, v60
	v_mul_f32_e32 v29, v29, v61
	v_cmp_le_i32_e32 vcc, 16, v70
	s_nop 1
	v_cndmask_b32_e32 v10, 0, v10, vcc
	v_cmp_le_i32_e32 vcc, 48, v70
	s_nop 1
	v_cndmask_b32_e32 v26, 0, v26, vcc
	v_cmp_le_i32_e32 vcc, 17, v70
	s_nop 1
	v_cndmask_b32_e32 v11, 0, v11, vcc
	v_cmp_le_i32_e32 vcc, 49, v70
	s_nop 1
	v_cndmask_b32_e32 v27, 0, v27, vcc
	v_cmp_le_i32_e32 vcc, 18, v70
	s_nop 1
	v_cndmask_b32_e32 v12, 0, v12, vcc
	v_cmp_le_i32_e32 vcc, 50, v70
	s_nop 1
	v_cndmask_b32_e32 v28, 0, v28, vcc
	v_cmp_le_i32_e32 vcc, 19, v70
	s_nop 1
	v_cndmask_b32_e32 v13, 0, v13, vcc
	v_cmp_le_i32_e32 vcc, 51, v70
	s_nop 1
	v_cndmask_b32_e32 v29, 0, v29, vcc
	s_waitcnt lgkmcnt(0)
	v_sub_f32_e32 v62, v127, v62
	v_sub_f32_e32 v63, v127, v63
	v_sub_f32_e32 v64, v127, v64
	v_sub_f32_e32 v65, v127, v65
	v_sub_f32_e32 v66, v127, v66
	v_sub_f32_e32 v67, v127, v67
	v_sub_f32_e32 v68, v127, v68
	v_sub_f32_e32 v69, v127, v69
	v_min_f32_e32 v62, 0, v62
	v_min_f32_e32 v63, 0, v63
	v_min_f32_e32 v64, 0, v64
	v_min_f32_e32 v65, 0, v65
	v_min_f32_e32 v66, 0, v66
	v_min_f32_e32 v67, 0, v67
	v_min_f32_e32 v68, 0, v68
	v_min_f32_e32 v69, 0, v69
	v_mul_f32_e32 v62, 0x3fb8aa3b, v62
	v_mul_f32_e32 v63, 0x3fb8aa3b, v63
	v_mul_f32_e32 v64, 0x3fb8aa3b, v64
	v_mul_f32_e32 v65, 0x3fb8aa3b, v65
	v_mul_f32_e32 v66, 0x3fb8aa3b, v66
	v_mul_f32_e32 v67, 0x3fb8aa3b, v67
	v_mul_f32_e32 v68, 0x3fb8aa3b, v68
	v_mul_f32_e32 v69, 0x3fb8aa3b, v69
	v_exp_f32_e32 v62, v62
	v_exp_f32_e32 v63, v63
	v_exp_f32_e32 v64, v64
	v_exp_f32_e32 v65, v65
	v_exp_f32_e32 v66, v66
	v_exp_f32_e32 v67, v67
	v_exp_f32_e32 v68, v68
	v_exp_f32_e32 v69, v69
	v_mul_f32_e32 v14, v14, v62
	v_mul_f32_e32 v30, v30, v63
	v_mul_f32_e32 v15, v15, v64
	v_mul_f32_e32 v31, v31, v65
	v_mul_f32_e32 v16, v16, v66
	v_mul_f32_e32 v32, v32, v67
	v_mul_f32_e32 v17, v17, v68
	v_mul_f32_e32 v33, v33, v69
	v_cmp_le_i32_e32 vcc, 24, v70
	s_nop 1
	v_cndmask_b32_e32 v14, 0, v14, vcc
	v_cmp_le_i32_e32 vcc, 56, v70
	s_nop 1
	v_cndmask_b32_e32 v30, 0, v30, vcc
	v_cmp_le_i32_e32 vcc, 25, v70
	s_nop 1
	v_cndmask_b32_e32 v15, 0, v15, vcc
	v_cmp_le_i32_e32 vcc, 57, v70
	s_nop 1
	v_cndmask_b32_e32 v31, 0, v31, vcc
	v_cmp_le_i32_e32 vcc, 26, v70
	s_nop 1
	v_cndmask_b32_e32 v16, 0, v16, vcc
	v_cmp_le_i32_e32 vcc, 58, v70
	s_nop 1
	v_cndmask_b32_e32 v32, 0, v32, vcc
	v_cmp_le_i32_e32 vcc, 27, v70
	s_nop 1
	v_cndmask_b32_e32 v17, 0, v17, vcc
	v_cmp_le_i32_e32 vcc, 59, v70
	s_nop 1
	v_cndmask_b32_e32 v33, 0, v33, vcc
	v_mov_b64_e32 v[50:51], v[2:3]
	v_mov_b64_e32 v[52:53], v[4:5]
	v_mov_b64_e32 v[54:55], v[6:7]
	v_mov_b64_e32 v[56:57], v[8:9]
	v_mov_b64_e32 v[58:59], v[10:11]
	v_mov_b64_e32 v[60:61], v[12:13]
	v_mov_b64_e32 v[62:63], v[14:15]
	v_mov_b64_e32 v[64:65], v[16:17]
	v_mov_b64_e32 v[2:3], v[18:19]
	v_mov_b64_e32 v[4:5], v[20:21]
	v_mov_b64_e32 v[6:7], v[22:23]
	v_mov_b64_e32 v[8:9], v[24:25]
	v_mov_b64_e32 v[10:11], v[26:27]
	v_mov_b64_e32 v[12:13], v[28:29]
	v_mov_b64_e32 v[14:15], v[30:31]
	v_mov_b64_e32 v[16:17], v[32:33]
	s_branch .LBB0_1039

; __device__ __forceinline__ float sigmoidf_(float x) { return 1.0f / (1.0f + __expf(-x)); }
; __device__ __forceinline__ float softplusf_(float x) { return fmaxf(x, 0.f) + __logf(1.0f + __expf(-fabsf(x))); }
; #define AIN(i) ld_ptr(c.la + 2 * (i))
; __device__ __forceinline__ void wy_prefetch(const Ctx& c, WyPre& P, int l, int tk, int lane, int wid) {
;     ...
;         for (int r = 0; r < 11; ++r) { const int rr = 8 * wid + r - 3;
;             P.hx[j][r] = (ch == 0 && rr < 0) ? (unsigned short)0 : __builtin_nontemporal_load(H + (size_t)((long long)row0 + rr) * HW + HGQKV + j * 512 + hh * 64 + lane); }
; __device__ __forceinline__ int wy_producer_task(const Ctx& c, int l, int tk, WyPre& P, unsigned* head) {
;     ...
;     if (wid == 0) { const float al = -__expf(((const float*)AIN(I_ALOG))[l * 8 + hh]), dt = ((const float*)AIN(I_DTB))[l * 8 + hh];
;         float g = al * softplusf_(P.sa + dt);
; #pragma unroll
;         for (int o = 1; o < 64; o <<= 1) { const float t = __shfl_up(g, o); if (lane >= o) g += t; }
;         GC[lane] = g; BE[lane] = sigmoidf_(P.sb); }
.LBB0_1093:
	ds_read_b32 v2, v1 offset:368
	s_and_b32 s1, s46, 7
	v_readlane_b32 s2, v254, 54
	s_or_b32 s30, s1, s2
	s_lshl_b64 s[2:3], s[30:31], 2
	s_waitcnt lgkmcnt(0)
	v_readfirstlane_b32 s6, v2
	ds_read_b32 v2, v1 offset:372
	s_add_u32 s6, s6, s2
	v_add_u32_e32 v6, -1, v223
	s_waitcnt lgkmcnt(0)
	v_readfirstlane_b32 s7, v2
	s_addc_u32 s7, s7, s3
	s_nop 3
	global_load_dword v2, v1, s[6:7]
	ds_read_b32 v3, v1 offset:376
	s_waitcnt lgkmcnt(0)
	v_readfirstlane_b32 s1, v3
	ds_read_b32 v3, v1 offset:380
	s_add_u32 s2, s1, s2
	s_mov_b32 s1, 0xbfb8aa3b
	s_waitcnt lgkmcnt(0)
	v_readfirstlane_b32 s6, v3
	s_addc_u32 s3, s6, s3
	global_load_dword v3, v1, s[2:3]
	s_waitcnt vmcnt(1)
	v_mul_f32_e32 v2, 0x3fb8aa3b, v2
	v_exp_f32_e32 v2, v2
	s_waitcnt vmcnt(0)
	v_add_f32_e32 v3, v111, v3
	v_max_f32_e32 v4, 0, v3
	v_mul_f32_e64 v3, |v3|, s1
	v_exp_f32_e32 v3, v3
	s_mov_b32 s1, 0x800000
	v_add_f32_e32 v3, 1.0, v3
	v_cmp_gt_f32_e32 vcc, s1, v3
	s_mov_b32 s1, 0x3f317217
	s_nop 0
	v_cndmask_b32_e64 v5, 0, 32, vcc
	v_ldexp_f32 v3, v3, v5
	v_log_f32_e32 v3, v3
	s_nop 0
	v_mul_f32_e32 v5, 0x3f317217, v3
	v_fma_f32 v5, v3, s1, -v5
	v_fmac_f32_e32 v5, 0x3377d1cf, v3
	s_mov_b32 s1, 0x7f800000
	v_fmac_f32_e32 v5, 0x3f317217, v3
	v_cmp_lt_f32_e64 s[2:3], |v3|, s1
	s_nop 1
	v_cndmask_b32_e64 v3, v3, v5, s[2:3]
	v_mov_b32_e32 v5, 0x41b17218
	v_cndmask_b32_e32 v5, 0, v5, vcc
	v_sub_f32_e32 v3, v3, v5
	v_and_b32_e32 v5, 64, v223
	v_cmp_lt_i32_e32 vcc, v6, v5
	v_add_f32_e32 v3, v4, v3
	v_mul_f32_e64 v4, v3, -v2
	v_cndmask_b32_e32 v6, v6, v223, vcc
	v_lshlrev_b32_e32 v6, 2, v6
	ds_bpermute_b32 v6, v6, v4
	v_cmp_gt_i32_e32 vcc, 1, v88
	s_waitcnt lgkmcnt(0)
	v_fma_f32 v2, v3, -v2, v6
	v_add_u32_e32 v3, -2, v223
	v_cndmask_b32_e32 v2, v2, v4, vcc
	v_cmp_lt_i32_e32 vcc, v3, v5
	s_nop 1
	v_cndmask_b32_e32 v3, v3, v223, vcc
	v_lshlrev_b32_e32 v3, 2, v3
	ds_bpermute_b32 v3, v3, v2
	v_cmp_gt_i32_e32 vcc, 2, v88
	s_waitcnt lgkmcnt(0)
	v_add_f32_e32 v3, v2, v3
	v_cndmask_b32_e32 v2, v3, v2, vcc
	v_add_u32_e32 v3, -4, v223
	v_cmp_lt_i32_e32 vcc, v3, v5
	s_nop 1
	v_cndmask_b32_e32 v3, v3, v223, vcc
	v_lshlrev_b32_e32 v3, 2, v3
	ds_bpermute_b32 v3, v3, v2
	v_cmp_gt_i32_e32 vcc, 4, v88
	s_waitcnt lgkmcnt(0)
	v_add_f32_e32 v3, v2, v3
	v_cndmask_b32_e32 v2, v3, v2, vcc
	v_add_u32_e32 v3, -8, v223
	v_cmp_lt_i32_e32 vcc, v3, v5
	s_nop 1
	v_cndmask_b32_e32 v3, v3, v223, vcc
	v_lshlrev_b32_e32 v3, 2, v3
	ds_bpermute_b32 v3, v3, v2
	v_cmp_gt_i32_e32 vcc, 8, v88
	s_waitcnt lgkmcnt(0)
	v_add_f32_e32 v3, v2, v3
	v_cndmask_b32_e32 v2, v3, v2, vcc
	v_add_u32_e32 v3, -16, v223
	v_cmp_lt_i32_e32 vcc, v3, v5
	s_nop 1
	v_cndmask_b32_e32 v3, v3, v223, vcc
	v_lshlrev_b32_e32 v3, 2, v3
	ds_bpermute_b32 v3, v3, v2
	v_cmp_gt_i32_e32 vcc, 16, v88
	s_waitcnt lgkmcnt(0)
	v_add_f32_e32 v3, v2, v3
	v_cndmask_b32_e32 v2, v3, v2, vcc
	v_subrev_u32_e32 v3, 32, v223
	v_cmp_lt_i32_e32 vcc, v3, v5
	s_nop 1
	v_cndmask_b32_e32 v3, v3, v223, vcc
	v_lshlrev_b32_e32 v3, 2, v3
	ds_bpermute_b32 v3, v3, v2
	v_cmp_gt_i32_e32 vcc, 32, v88
	s_waitcnt lgkmcnt(0)
	v_add_f32_e32 v3, v2, v3
	v_cndmask_b32_e32 v2, v3, v2, vcc
	v_lshl_add_u32 v3, v88, 2, 0
	v_add_u32_e32 v4, 0x11b00, v3
	ds_write_b32 v4, v2
	v_mul_f32_e32 v2, 0xbfb8aa3b, v109
	v_exp_f32_e32 v2, v2
	v_add_u32_e32 v3, 0x11c00, v3
	v_add_f32_e32 v2, 1.0, v2
	v_div_scale_f32 v4, s[2:3], v2, v2, 1.0
	v_rcp_f32_e32 v5, v4
	s_nop 0
	v_fma_f32 v6, -v4, v5, 1.0
	v_fmac_f32_e32 v5, v6, v5
	v_div_scale_f32 v6, vcc, 1.0, v2, 1.0
	v_mul_f32_e32 v7, v6, v5
	v_fma_f32 v8, -v4, v7, v6
	v_fmac_f32_e32 v7, v8, v5
	v_fma_f32 v4, -v4, v7, v6
	v_div_fmas_f32 v4, v4, v5, v7
	v_div_fixup_f32 v2, v4, v2, 1.0
	ds_write_b32 v3, v2
	s_and_saveexec_b64 s[2:3], s[4:5]
	s_cbranch_execnz .LBB0_966
	s_branch .LBB0_967
.LBB0_1096:
	s_add_u32 s4, s10, s79
	s_addc_u32 s5, s11, s56
	s_mulk_i32 s5, 0x1c00
	s_mul_hi_u32 s8, s4, 0x1c00
	s_add_i32 s8, s8, s5
	s_mulk_i32 s4, 0x1c00
	s_add_u32 s4, s19, s4
	s_addc_u32 s5, s22, s8
	s_lshl_b32 s8, s20, 1
	s_add_u32 s4, s4, s8
	s_addc_u32 s5, s5, 0
	v_lshl_add_u64 v[44:45], v[88:89], 1, s[4:5]
	v_add_co_u32_e32 v44, vcc, 0xfd01000, v44
	s_nop 1
	v_addc_co_u32_e32 v45, vcc, 0, v45, vcc
	global_load_ushort v98, v[44:45], off offset:512 nt
	s_and_b64 vcc, exec, s[6:7]
	s_cbranch_vccnz .LBB0_1075
